# P8 last half round: the 128 leftover units are split by rows between workgroup c and the idle c+128 (same body, ai=1 MFMAs and epilogue half skipped)
# speedup vs baseline: 1.0003x; 1.0003x over previous
;     __device__ bool next(int i, Unit& u) const { if (i > 1 || !so.next(0, u)) return false; if (i == 1) { u.pm += 64; u.pn += 4; } return true; }
; #define LAS __attribute__((address_space(3)))
; __device__ __forceinline__ float rstd_row(const float* rowp, int row) {
;     const f32x4* p = (const f32x4*)(rowp + (size_t)row * 16); const f32x4 a = p[0], b = p[1], c = p[2], d = p[3];
;     const float s = (((a[0] + a[1]) + (a[2] + a[3])) + ((b[0] + b[1]) + (b[2] + b[3]))) + (((c[0] + c[1]) + (c[2] + c[3])) + ((d[0] + d[1]) + (d[2] + d[3])));
;     return 1.0f / sqrtf(s * (1.0f / 1024.0f) + 1e-6f);
; }
; __global__ void __launch_bounds__(512, 2) hybrid_fwd(Args args) {
;     ...
;     if (IN(8)) { pg8::StaticOrder S; S.init(M, NFF, G, blk); pg8::Unit u0; u0.pm = 0; u0.pn = 0; S.next(0, u0); const int bb = u0.pm >> 5;
;         LAS float* rsl = (LAS float*)(lds + 131072 + 1024);
;         LAS float* bl = (LAS float*)(lds + 131072 + 2048);
;         if (tid < 256) { rsl[tid] = pg8::rstd_row(ROWP3, u0.pm * 256 + tid); pg8::Unit uu; for (int i = 0; S.next(i, uu); ++i) bl[i * 256 + tid] = BIAS[(size_t)bb * NBIAS + NIN + uu.pn * 256 + tid]; }
;         __syncthreads();
.LBB0_885:
	s_mov_b32 s99, 0
	s_mov_b32 s100, 0
	s_mov_b32 s98, 0
	s_mov_b32 s101, 0
	s_cmp_lt_i32 s82, 9
	s_cselect_b64 s[6:7], -1, 0
	s_and_b64 s[6:7], s[6:7], s[4:5]
	s_andn2_b64 vcc, exec, s[6:7]
	s_cbranch_vccnz .LBB0_914
	s_cmpk_lt_i32 s2, 0x580
	s_cselect_b64 s[4:5], -1, 0
	s_cmpk_gt_i32 s2, 0x57f
	s_mov_b32 s14, 0
	s_cbranch_scc1 .LBB0_888
	s_ashr_i32 s3, s2, 31
	s_lshr_b32 s3, s3, 29
	s_add_i32 s3, s2, s3
	s_ashr_i32 s10, s3, 3
	s_and_b32 s3, s3, -8
	s_sub_i32 s3, s2, s3
	s_cmp_lt_i32 s3, 0
	s_movk_i32 s11, 0xb1
	s_cselect_b32 s11, s11, 0xb0
	s_mul_i32 s3, s3, s11
	s_add_i32 s3, s3, s10
	s_mul_hi_i32 s10, s3, 0x2e8ba2e9
	s_lshr_b32 s11, s10, 31
	s_ashr_i32 s10, s10, 5
	s_add_i32 s10, s10, s11
	s_lshl_b32 s11, s10, 3
	s_mulk_i32 s10, 0xb0
	s_sub_i32 s3, s3, s10
	s_bfe_u32 s10, s3, 0x3001c
	s_add_i32 s10, s3, s10
	s_and_b32 s10, s10, 0xfff8
	s_sub_i32 s3, s3, s10
	s_sext_i32_i16 s3, s3
	s_add_i32 s14, s11, s3
.LBB0_888:
	s_ashr_i32 s10, s14, 5
	s_movk_i32 s11, 0xff
	s_ashr_i32 s3, s2, 31
	v_cmp_lt_i32_e32 vcc, s11, v162
	s_and_saveexec_b64 s[12:13], vcc
	s_xor_b64 s[12:13], exec, s[12:13]
	s_ashr_i32 s11, s10, 31
	s_or_saveexec_b64 s[12:13], s[12:13]
	s_waitcnt lgkmcnt(0)
	v_mov_b64_e32 v[0:1], s[10:11]
	s_xor_b64 exec, exec, s[12:13]
	s_cbranch_execz .LBB0_898
	v_lshl_add_u32 v0, s14, 8, v162
	v_ashrrev_i32_e32 v1, 31, v0
	v_lshlrev_b64 v[0:1], 6, v[0:1]
	v_lshl_add_u64 v[0:1], s[0:1], 0, v[0:1]
	global_load_dwordx4 v[4:7], v[0:1], off
	global_load_dwordx4 v[8:11], v[0:1], off offset:32
	global_load_dwordx4 v[12:15], v[0:1], off offset:16
	global_load_dwordx4 v[16:19], v[0:1], off offset:48
	s_mul_i32 s20, s10, 0x9800
	s_lshr_b32 s21, s2, 6
	s_lshl_b32 s21, s21, 10
	s_add_i32 s20, s20, s21
	s_add_i32 s20, s20, 0x4000
	s_add_u32 s20, s67, s20
	s_addc_u32 s21, s66, 0
	v_lshlrev_b32_e32 v26, 2, v162
	global_load_dword v27, v26, s[20:21]
	s_add_u32 s20, s20, 0x1000
	s_addc_u32 s21, s21, 0
	global_load_dword v28, v26, s[20:21]
	s_add_u32 s20, s20, 0x1000
	s_addc_u32 s21, s21, 0
	global_load_dword v29, v26, s[20:21]
	s_add_u32 s20, s20, 0x1000
	s_addc_u32 s21, s21, 0
	global_load_dword v30, v26, s[20:21]
	s_add_u32 s20, s20, 0x1000
	s_addc_u32 s21, s21, 0
	global_load_dword v31, v26, s[20:21]
	s_add_u32 s20, s20, 0x1000
	s_addc_u32 s21, s21, 0
	s_cmp_gt_u32 s2, 0x7f
	s_cselect_b32 s98, 0x800, 0
	s_sub_u32 s20, s20, s98
	s_subb_u32 s21, s21, 0
	s_mov_b32 s98, 0
	global_load_dword v32, v26, s[20:21]
	v_mov_b32_e32 v22, 0x358637bd
	s_mov_b32 s1, 0xf800000
	s_ashr_i32 s16, s42, 31
	s_ashr_i32 s11, s10, 31
	s_mul_i32 s0, s10, 0x9800
	s_mul_hi_i32 s19, s10, 0x9800
	s_add_u32 s0, s67, s0
	v_ashrrev_i32_e32 v163, 31, v162
	v_mov_b32_e32 v23, 0x260
	v_lshl_add_u32 v24, v162, 2, 0
	s_mov_b64 s[14:15], 0x4000
	s_mov_b32 s17, s42
	s_movk_i32 s18, 0xb1
	v_mov_b64_e32 v[0:1], 0x580
	v_mov_b64_e32 v[2:3], 0x57f
	v_add_u32_e32 v25, 0x20400, v24
	s_waitcnt vmcnt(0)
	v_mov_b32_e32 v20, v4
	v_mov_b32_e32 v21, v8
	v_mov_b32_e32 v8, v5
	v_mov_b32_e32 v4, v6
	v_mov_b32_e32 v5, v10
	v_mov_b32_e32 v10, v7
	v_mov_b32_e32 v6, v12
	v_mov_b32_e32 v7, v16
	v_mov_b32_e32 v16, v13
	v_mov_b32_e32 v12, v14
	v_mov_b32_e32 v13, v18
	v_mov_b32_e32 v18, v15
	v_pk_add_f32 v[8:9], v[20:21], v[8:9]
	v_pk_add_f32 v[4:5], v[4:5], v[10:11]
	v_pk_add_f32 v[6:7], v[6:7], v[16:17]
	v_pk_add_f32 v[10:11], v[12:13], v[18:19]
	v_pk_add_f32 v[4:5], v[8:9], v[4:5]
	v_pk_add_f32 v[6:7], v[6:7], v[10:11]
	s_nop 0
	v_pk_add_f32 v[4:5], v[4:5], v[6:7]
	v_add_u32_e32 v6, 0x20800, v24
	v_add_f32_e32 v4, v4, v5
	v_fmac_f32_e32 v22, 0x3a800000, v4
	v_mul_f32_e32 v4, 0x4f800000, v22
	v_cmp_gt_f32_e32 vcc, s1, v22
	s_addc_u32 s1, s66, s19
	s_nop 0
	v_cndmask_b32_e32 v7, v22, v4, vcc
	v_sqrt_f32_e32 v8, v7
	v_lshl_add_u64 v[4:5], v[162:163], 2, s[0:1]
	v_lshl_add_u64 v[4:5], v[4:5], 0, s[14:15]
	s_mov_b64 s[14:15], s[2:3]
	v_add_u32_e32 v9, -1, v8
	v_add_u32_e32 v10, 1, v8
	v_fma_f32 v11, -v9, v8, v7
	v_fma_f32 v12, -v10, v8, v7
	v_cmp_ge_f32_e64 s[0:1], 0, v11
	s_nop 1
	v_cndmask_b32_e64 v8, v8, v9, s[0:1]
	v_cmp_lt_f32_e64 s[0:1], 0, v12
	s_nop 1
	v_cndmask_b32_e64 v8, v8, v10, s[0:1]
	v_mul_f32_e32 v9, 0x37800000, v8
	v_cndmask_b32_e32 v8, v8, v9, vcc
	v_cmp_class_f32_e32 vcc, v7, v23
	s_nop 1
	v_cndmask_b32_e32 v7, v8, v7, vcc
	v_div_scale_f32 v8, s[0:1], v7, v7, 1.0
	v_rcp_f32_e32 v9, v8
	v_div_scale_f32 v10, vcc, 1.0, v7, 1.0
	v_fma_f32 v11, -v8, v9, 1.0
	v_fmac_f32_e32 v9, v11, v9
	v_mul_f32_e32 v11, v10, v9
	v_fma_f32 v12, -v8, v11, v10
	v_fmac_f32_e32 v11, v12, v9
	v_fma_f32 v8, -v8, v11, v10
	v_div_fmas_f32 v8, v8, v9, v11
	v_div_fixup_f32 v7, v8, v7, 1.0
	ds_write_b32 v25, v7
	ds_write_b32 v6, v27
	ds_write_b32 v6, v28 offset:1024
	ds_write_b32 v6, v29 offset:2048
	ds_write_b32 v6, v30 offset:3072
	ds_write_b32 v6, v31 offset:4096
	ds_write_b32 v6, v32 offset:5120

;     __device__ bool next(int i, Unit& u) const { if (i > 1 || !so.next(0, u)) return false; if (i == 1) { u.pm += 64; u.pn += 4; } return true; }
;     __host__ __device__ bool next(int i, Unit& u) const {
;         const long L = (long)i * G + c; if (L >= nwg) return false;
;         int wgid = (int)L; { const int q = nwg / NXCD, r = nwg % NXCD, xcd = wgid % NXCD, off = wgid / NXCD; wgid = (xcd < r ? xcd * (q + 1) : r * (q + 1) + (xcd - r) * q) + off; }
;         const int nig = WGM * nN, gid = wgid / nig, fm = gid * WGM, gsz = (nM - fm) < WGM ? (nM - fm) : WGM;
;         u.pm = fm + ((wgid % nig) % gsz); u.pn = (wgid % nig) / gsz; return true;
;     }
; template <class Epi, class Sched, bool ALIGN_EPI = false, bool SP2 = false>
; __device__ __forceinline__ void gemm_phase(PG8_LAS unsigned char* lds, const Gemm g, const Sched& S, const Epi& E) {
;     ...
;         for (int a = 0; a < 2; ++a)
; #pragma unroll
;             for (int b = 0; b < 2; ++b)
; #pragma unroll
;                 for (int m = 0; m < 4; ++m)
; #pragma unroll
;                     for (int n = 0; n < 2; ++n) acc[a][b][m][n] = (f32x4){0.f, 0.f, 0.f, 0.f};
;         }
;         cur = nxt; cA = nA; cB = nB; ++ui;
.LBB0_903:
	s_andn2_b64 vcc, exec, s[4:5]
	s_mov_b32 s57, s20
	s_mov_b32 s30, s22
	s_mov_b32 s99, s98
	s_mov_b32 s100, s101
	v_mov_b64_e32 v[0:1], v[162:163]
	s_mov_b64 s[36:37], s[28:29]
	s_cbranch_vccz .LBB0_913
.LBB0_904:
	s_add_i32 s47, s47, 1
	s_mul_i32 s4, s47, s50
	s_mul_hi_u32 s5, s47, s51
	s_add_i32 s5, s5, s4
	s_mul_i32 s4, s47, s51
	s_add_u32 s28, s4, s2
	s_addc_u32 s29, s5, s3
	s_mov_b32 s98, 0
	s_mov_b32 s101, 0
	s_cmp_lg_u32 s47, 5
	s_cbranch_scc1 .Lp8_sched_full
	s_cmp_lg_u32 s42, 0x100
	s_cbranch_scc1 .Lp8_sched_full
	s_mov_b32 s98, 1
	s_cmp_lt_u32 s2, 0x80
	s_cbranch_scc1 .Lp8_sched_full
	s_movk_i32 s101, 0x80
	s_sub_u32 s28, s28, 0x80
	s_subb_u32 s29, s29, 0
.Lp8_sched_full:
	v_cmp_gt_i64_e32 vcc, s[28:29], v[160:161]
	v_cmp_lt_i64_e64 s[4:5], s[28:29], v[158:159]
	s_cbranch_vccnz .LBB0_906
	s_ashr_i32 s20, s28, 31
	s_lshr_b32 s20, s20, 29
	s_add_i32 s20, s28, s20
	s_ashr_i32 s21, s20, 3
	s_and_b32 s20, s20, -8
	s_sub_i32 s20, s28, s20
	s_cmp_lt_i32 s20, 0
	s_cselect_b32 s22, s41, 0xb0
	s_mul_i32 s20, s20, s22
	s_add_i32 s20, s20, s21
	s_mul_hi_i32 s21, s20, 0x2e8ba2e9
	s_lshr_b32 s22, s21, 31
	s_ashr_i32 s21, s21, 5
	s_add_i32 s21, s21, s22
	s_lshl_b32 s22, s21, 3
	s_sub_i32 s23, 64, s22
	s_min_i32 s23, s23, 8
	s_abs_i32 s28, s23
	v_cvt_f32_u32_e32 v2, s28
	s_sub_i32 s38, 0, s28
	s_mulk_i32 s21, 0xb0
	s_sub_i32 s21, s20, s21
	v_rcp_iflag_f32_e32 v2, v2
	s_abs_i32 s20, s21
	s_xor_b32 s29, s21, s23
	s_ashr_i32 s29, s29, 31
	v_mul_f32_e32 v2, 0x4f7ffffe, v2
	v_cvt_u32_f32_e32 v2, v2
	s_nop 0
	v_readfirstlane_b32 s39, v2
	s_mul_i32 s38, s38, s39
	s_mul_hi_u32 s38, s39, s38
	s_add_i32 s39, s39, s38
	s_mul_hi_u32 s38, s20, s39
	s_mul_i32 s39, s38, s28
	s_sub_i32 s20, s20, s39
	s_add_i32 s58, s38, 1
	s_sub_i32 s39, s20, s28
	s_cmp_ge_u32 s20, s28
	s_cselect_b32 s38, s58, s38
	s_cselect_b32 s20, s39, s20
	s_add_i32 s39, s38, 1
	s_cmp_ge_u32 s20, s28
	s_cselect_b32 s20, s39, s38
	s_xor_b32 s20, s20, s29
	s_sub_i32 s20, s20, s29
	s_mul_i32 s23, s20, s23
	s_sub_i32 s21, s21, s23
	s_add_i32 s22, s22, s21
.LBB0_906:
	s_ashr_i32 s23, s22, 31
	s_lshl_b64 s[28:29], s[22:23], 19
	s_add_u32 s28, s24, s28
	s_addc_u32 s29, s25, s29
	s_lshl_b32 s38, s101, 11
	s_add_u32 s28, s28, s38
	s_addc_u32 s29, s29, 0
	s_and_b64 s[38:39], s[4:5], exec
	s_cselect_b32 s23, s29, s37
	s_cselect_b32 s58, s28, s36
	s_ashr_i32 s21, s20, 31
	s_lshl_b64 s[38:39], s[20:21], 19
	v_lshl_add_u64 v[162:163], v[144:145], 0, s[38:39]
	v_cndmask_b32_e64 v128, v0, v162, s[4:5]
	s_add_u32 s36, s36, 0x40080
	v_lshl_add_u64 v[130:131], v[0:1], 0, s[18:19]
	v_mov_b32_e32 v0, 0
	v_cndmask_b32_e64 v129, v1, v163, s[4:5]
	s_addc_u32 s37, s37, 0
	s_mov_b32 s21, -2
	v_mov_b32_e32 v1, v0
	v_mov_b32_e32 v2, v0
	v_mov_b32_e32 v3, v0
	v_mov_b32_e32 v4, v0
	v_mov_b32_e32 v5, v0
	v_mov_b32_e32 v6, v0
	v_mov_b32_e32 v7, v0
	v_mov_b32_e32 v16, v0
	v_mov_b32_e32 v17, v0
	v_mov_b32_e32 v18, v0
	v_mov_b32_e32 v19, v0
	v_mov_b32_e32 v20, v0
	v_mov_b32_e32 v21, v0
	v_mov_b32_e32 v22, v0
	v_mov_b32_e32 v23, v0
	v_mov_b32_e32 v32, v0
	v_mov_b32_e32 v33, v0
	v_mov_b32_e32 v34, v0
	v_mov_b32_e32 v35, v0
	v_mov_b32_e32 v36, v0
	v_mov_b32_e32 v37, v0
	v_mov_b32_e32 v38, v0
	v_mov_b32_e32 v39, v0
	v_mov_b32_e32 v48, v0
	v_mov_b32_e32 v49, v0
	v_mov_b32_e32 v50, v0
	v_mov_b32_e32 v51, v0
	v_mov_b32_e32 v52, v0
	v_mov_b32_e32 v53, v0
	v_mov_b32_e32 v54, v0
	v_mov_b32_e32 v55, v0
	v_mov_b32_e32 v8, v0
	v_mov_b32_e32 v9, v0
	v_mov_b32_e32 v10, v0
	v_mov_b32_e32 v11, v0
	v_mov_b32_e32 v12, v0
	v_mov_b32_e32 v13, v0
	v_mov_b32_e32 v14, v0
	v_mov_b32_e32 v15, v0
	v_mov_b32_e32 v24, v0
	v_mov_b32_e32 v25, v0
	v_mov_b32_e32 v26, v0
	v_mov_b32_e32 v27, v0
	v_mov_b32_e32 v28, v0
	v_mov_b32_e32 v29, v0
	v_mov_b32_e32 v30, v0
	v_mov_b32_e32 v31, v0
	v_mov_b32_e32 v40, v0
	v_mov_b32_e32 v41, v0
	v_mov_b32_e32 v42, v0
	v_mov_b32_e32 v43, v0
	v_mov_b32_e32 v44, v0
	v_mov_b32_e32 v45, v0
	v_mov_b32_e32 v46, v0
	v_mov_b32_e32 v47, v0
	v_mov_b32_e32 v56, v0
	v_mov_b32_e32 v57, v0
	v_mov_b32_e32 v58, v0
	v_mov_b32_e32 v59, v0
	v_mov_b32_e32 v60, v0
	v_mov_b32_e32 v61, v0
	v_mov_b32_e32 v62, v0
	v_mov_b32_e32 v63, v0
	v_mov_b32_e32 v64, v0
	v_mov_b32_e32 v65, v0
	v_mov_b32_e32 v66, v0
	v_mov_b32_e32 v67, v0
	v_mov_b32_e32 v68, v0
	v_mov_b32_e32 v69, v0
	v_mov_b32_e32 v70, v0
	v_mov_b32_e32 v71, v0
	v_mov_b32_e32 v80, v0
	v_mov_b32_e32 v81, v0
	v_mov_b32_e32 v82, v0
	v_mov_b32_e32 v83, v0
	v_mov_b32_e32 v84, v0
	v_mov_b32_e32 v85, v0
	v_mov_b32_e32 v86, v0
	v_mov_b32_e32 v87, v0
	v_mov_b32_e32 v96, v0
	v_mov_b32_e32 v97, v0
	v_mov_b32_e32 v98, v0
	v_mov_b32_e32 v99, v0
	v_mov_b32_e32 v100, v0
	v_mov_b32_e32 v101, v0
	v_mov_b32_e32 v102, v0
	v_mov_b32_e32 v103, v0
	v_mov_b32_e32 v112, v0
	v_mov_b32_e32 v113, v0
	v_mov_b32_e32 v114, v0
	v_mov_b32_e32 v115, v0
	v_mov_b32_e32 v116, v0
	v_mov_b32_e32 v117, v0
	v_mov_b32_e32 v118, v0
	v_mov_b32_e32 v119, v0
	v_mov_b32_e32 v72, v0
	v_mov_b32_e32 v73, v0
	v_mov_b32_e32 v74, v0
	v_mov_b32_e32 v75, v0
	v_mov_b32_e32 v76, v0
	v_mov_b32_e32 v77, v0
	v_mov_b32_e32 v78, v0
	v_mov_b32_e32 v79, v0
	v_mov_b32_e32 v88, v0
	v_mov_b32_e32 v89, v0
	v_mov_b32_e32 v90, v0
	v_mov_b32_e32 v91, v0
	v_mov_b32_e32 v92, v0
	v_mov_b32_e32 v93, v0
	v_mov_b32_e32 v94, v0
	v_mov_b32_e32 v95, v0
	v_mov_b32_e32 v104, v0
	v_mov_b32_e32 v105, v0
	v_mov_b32_e32 v106, v0
	v_mov_b32_e32 v107, v0
	v_mov_b32_e32 v108, v0
	v_mov_b32_e32 v109, v0
	v_mov_b32_e32 v110, v0
	v_mov_b32_e32 v111, v0
	v_mov_b32_e32 v120, v0
	v_mov_b32_e32 v121, v0
	v_mov_b32_e32 v122, v0
	v_mov_b32_e32 v123, v0
	v_mov_b32_e32 v124, v0
	v_mov_b32_e32 v125, v0
	v_mov_b32_e32 v126, v0
	v_mov_b32_e32 v127, v0
; #define PG8_STAGE(bufoff, gbase, voff) do { _Pragma("unroll") for (int _i = 0; _i < 2; ++_i) \
;         __builtin_amdgcn_global_load_lds((const unsigned*)((const char*)(gbase) + (voff)[_i]), (PG8_LAS unsigned*)(lds + (bufoff) + ldsw + _i * 8192), 16, 0, 0); } while (0)
; #define PG8_LDA(dst, b, h) do { _Pragma("unroll") for (int m = 0; m < 4; ++m) _Pragma("unroll") for (int k = 0; k < 2; ++k) dst[m][k] = *(const PG8_LAS bf16x8*)(lds + PG8_SA(b, h) + aoff + m * 2048 + k * 1024); } while (0)
; #define PG8_LDB(dst, b, h) do { _Pragma("unroll") for (int n = 0; n < 2; ++n) _Pragma("unroll") for (int k = 0; k < 2; ++k) dst[n][k] = *(const PG8_LAS bf16x8*)(lds + PG8_SB(b, h) + boff + n * 2048 + k * 1024); } while (0)
; #define PG8_MMA(ai, bj, At, Bt) do { __builtin_amdgcn_s_setprio(1); _Pragma("unroll") for (int m = 0; m < 4; ++m) _Pragma("unroll") for (int n = 0; n < 2; ++n) _Pragma("unroll") for (int k = 0; k < 2; ++k) \
;         acc[ai][bj][m][n] = __builtin_amdgcn_mfma_f32_16x16x32_bf16(Bt[n][k], At[m][k], acc[ai][bj][m][n], 0, 0, 0); __builtin_amdgcn_s_setprio(0); } while (0)
; #define PG8_WAIT_V(n) asm volatile("s_waitcnt vmcnt(" #n ")" ::: "memory")
; #define PG8_WAIT_L(n) asm volatile("s_waitcnt lgkmcnt(" #n ")" ::: "memory")
; #define PG8_BAR __builtin_amdgcn_s_barrier()
; #define PG8_SCHED __builtin_amdgcn_sched_barrier(0)
; template <class Epi, class Sched, bool ALIGN_EPI = false, bool SP2 = false>
; __device__ __forceinline__ void gemm_phase(PG8_LAS unsigned char* lds, const Gemm g, const Sched& S, const Epi& E) {
;     ...
;             PG8_LDB(B0, 0, 0); PG8_LDB(B1, 0, 1); PG8_SCHED; PG8_LDA(At, 0, 0); PG8_STAGE(PG8_SA(1, 1), a1 + hstep, voffA);
;             PG8_WAIT_V(8); PG8_WAIT_L(0); PG8_BAR; PG8_MMA(0, 0, At, B0); PG8_MMA(0, 1, At, B1); PG8_BAR; PG8_SCHED;
;             PG8_LDA(At, 0, 1); PG8_STAGE(PG8_SB(0, 0), b2, voffB); PG8_STAGE(PG8_SB(0, 1), b2 + hstep, voffB); PG8_STAGE(PG8_SA(0, 0), a2, voffA);
;             PG8_WAIT_V(8); PG8_WAIT_L(0); PG8_BAR; PG8_MMA(1, 0, At, B0); PG8_MMA(1, 1, At, B1); PG8_BAR; PG8_SCHED;
.LBB0_907:
	ds_read_b128 v[132:135], v171
	ds_read_b128 v[136:139], v171 offset:1024
	ds_read_b128 v[140:143], v171 offset:2048
	ds_read_b128 v[174:177], v171 offset:3072
	ds_read_b128 v[178:181], v172
	ds_read_b128 v[182:185], v172 offset:1024
	ds_read_b128 v[186:189], v172 offset:2048
	ds_read_b128 v[190:193], v172 offset:3072
	s_add_u32 s59, s36, 0xfffc0080
	s_addc_u32 s60, s37, -1
	s_cmp_eq_u32 s21, 12
	s_cselect_b64 vcc, -1, 0
	s_and_b64 s[38:39], vcc, exec
	v_cndmask_b32_e32 v165, v131, v129, vcc
	s_cselect_b32 s39, s23, s60
	s_cselect_b32 s38, s58, s59
	v_cndmask_b32_e32 v164, v130, v128, vcc
	s_mov_b32 m0, s55
	v_lshl_add_u64 v[228:229], s[36:37], 0, v[154:155]
	ds_read_b128 v[194:197], v173
	ds_read_b128 v[198:201], v173 offset:1024
	ds_read_b128 v[202:205], v173 offset:2048
	ds_read_b128 v[206:209], v173 offset:3072
	ds_read_b128 v[210:213], v173 offset:4096
	ds_read_b128 v[214:217], v173 offset:5120
	ds_read_b128 v[218:221], v173 offset:6144
	ds_read_b128 v[222:225], v173 offset:7168
	global_load_lds_dwordx4 v[228:229], off
	v_lshl_add_u64 v[228:229], s[36:37], 0, v[156:157]
	s_mov_b32 m0, s56
	s_nop 0
	global_load_lds_dwordx4 v[228:229], off
	s_waitcnt vmcnt(8)
	s_waitcnt lgkmcnt(0)
	s_barrier
	s_setprio 1
	s_waitcnt lgkmcnt(0)
	v_mfma_f32_16x16x32_bf16 v[124:127], v[132:135], v[194:197], v[124:127]
	v_mfma_f32_16x16x32_bf16 v[120:123], v[140:143], v[194:197], v[120:123]
	v_mfma_f32_16x16x32_bf16 v[108:111], v[132:135], v[202:205], v[108:111]
	v_mfma_f32_16x16x32_bf16 v[104:107], v[140:143], v[202:205], v[104:107]
	v_mfma_f32_16x16x32_bf16 v[92:95], v[132:135], v[210:213], v[92:95]
	v_mfma_f32_16x16x32_bf16 v[88:91], v[140:143], v[210:213], v[88:91]
	v_mfma_f32_16x16x32_bf16 v[76:79], v[132:135], v[218:221], v[76:79]
	v_mfma_f32_16x16x32_bf16 v[72:75], v[140:143], v[218:221], v[72:75]
	v_mfma_f32_16x16x32_bf16 v[124:127], v[136:139], v[198:201], v[124:127]
	v_mfma_f32_16x16x32_bf16 v[120:123], v[174:177], v[198:201], v[120:123]
	v_mfma_f32_16x16x32_bf16 v[108:111], v[136:139], v[206:209], v[108:111]
	v_mfma_f32_16x16x32_bf16 v[104:107], v[174:177], v[206:209], v[104:107]
	v_mfma_f32_16x16x32_bf16 v[92:95], v[136:139], v[214:217], v[92:95]
	v_mfma_f32_16x16x32_bf16 v[88:91], v[174:177], v[214:217], v[88:91]
	v_mfma_f32_16x16x32_bf16 v[76:79], v[136:139], v[222:225], v[76:79]
	v_mfma_f32_16x16x32_bf16 v[72:75], v[174:177], v[222:225], v[72:75]
	s_setprio 0
	s_setprio 1
	v_mfma_f32_16x16x32_bf16 v[116:119], v[178:181], v[194:197], v[116:119]
	v_mfma_f32_16x16x32_bf16 v[112:115], v[186:189], v[194:197], v[112:115]
	v_mfma_f32_16x16x32_bf16 v[100:103], v[178:181], v[202:205], v[100:103]
	v_mfma_f32_16x16x32_bf16 v[96:99], v[186:189], v[202:205], v[96:99]
	v_mfma_f32_16x16x32_bf16 v[84:87], v[178:181], v[210:213], v[84:87]
	v_mfma_f32_16x16x32_bf16 v[80:83], v[186:189], v[210:213], v[80:83]
	v_mfma_f32_16x16x32_bf16 v[68:71], v[178:181], v[218:221], v[68:71]
	v_mfma_f32_16x16x32_bf16 v[64:67], v[186:189], v[218:221], v[64:67]
	v_mfma_f32_16x16x32_bf16 v[116:119], v[182:185], v[198:201], v[116:119]
	v_mfma_f32_16x16x32_bf16 v[112:115], v[190:193], v[198:201], v[112:115]
	v_mfma_f32_16x16x32_bf16 v[100:103], v[182:185], v[206:209], v[100:103]
	v_mfma_f32_16x16x32_bf16 v[96:99], v[190:193], v[206:209], v[96:99]
	v_mfma_f32_16x16x32_bf16 v[84:87], v[182:185], v[214:217], v[84:87]
	v_mfma_f32_16x16x32_bf16 v[80:83], v[190:193], v[214:217], v[80:83]
	v_mfma_f32_16x16x32_bf16 v[68:71], v[182:185], v[222:225], v[68:71]
	v_mfma_f32_16x16x32_bf16 v[64:67], v[190:193], v[222:225], v[64:67]
	s_setprio 0
	s_barrier
	s_add_i32 s59, s52, s40
	v_lshl_add_u64 v[228:229], v[164:165], 0, v[150:151]
	s_mov_b32 m0, s59
	ds_read_b128 v[194:197], v173 offset:16384
	ds_read_b128 v[198:201], v173 offset:17408
	ds_read_b128 v[202:205], v173 offset:18432
	ds_read_b128 v[206:209], v173 offset:19456
	ds_read_b128 v[210:213], v173 offset:20480
	ds_read_b128 v[214:217], v173 offset:21504
	ds_read_b128 v[218:221], v173 offset:22528
	ds_read_b128 v[222:225], v173 offset:23552
	global_load_lds_dwordx4 v[228:229], off
	v_lshl_add_u64 v[230:231], v[164:165], 0, v[146:147]
	s_add_i32 m0, s59, 0x2000
	v_lshl_add_u64 v[232:233], v[164:165], 0, s[0:1]
	s_add_i32 s59, s53, s40
	global_load_lds_dwordx4 v[230:231], off
	v_lshl_add_u64 v[234:235], v[232:233], 0, v[150:151]
	s_mov_b32 m0, s59
	v_lshl_add_u64 v[232:233], v[232:233], 0, v[146:147]
	global_load_lds_dwordx4 v[234:235], off
	s_add_i32 m0, s59, 0x2000
	v_lshl_add_u64 v[234:235], s[38:39], 0, v[148:149]
	global_load_lds_dwordx4 v[232:233], off
	v_lshl_add_u64 v[232:233], s[38:39], 0, v[152:153]
	s_mov_b32 m0, s31
	s_nop 0
	global_load_lds_dwordx4 v[232:233], off
	s_mov_b32 m0, s44
	s_nop 0
	global_load_lds_dwordx4 v[234:235], off
	s_waitcnt vmcnt(8)
	s_waitcnt lgkmcnt(0)
	s_barrier
	s_cmp_lg_u32 s99, 0
	s_cbranch_scc1 .Lp8_skip1
; #define PG8_STAGE(bufoff, gbase, voff) do { _Pragma("unroll") for (int _i = 0; _i < 2; ++_i) \
;         __builtin_amdgcn_global_load_lds((const unsigned*)((const char*)(gbase) + (voff)[_i]), (PG8_LAS unsigned*)(lds + (bufoff) + ldsw + _i * 8192), 16, 0, 0); } while (0)
; #define PG8_LDA(dst, b, h) do { _Pragma("unroll") for (int m = 0; m < 4; ++m) _Pragma("unroll") for (int k = 0; k < 2; ++k) dst[m][k] = *(const PG8_LAS bf16x8*)(lds + PG8_SA(b, h) + aoff + m * 2048 + k * 1024); } while (0)
; #define PG8_LDB(dst, b, h) do { _Pragma("unroll") for (int n = 0; n < 2; ++n) _Pragma("unroll") for (int k = 0; k < 2; ++k) dst[n][k] = *(const PG8_LAS bf16x8*)(lds + PG8_SB(b, h) + boff + n * 2048 + k * 1024); } while (0)
; #define PG8_MMA(ai, bj, At, Bt) do { __builtin_amdgcn_s_setprio(1); _Pragma("unroll") for (int m = 0; m < 4; ++m) _Pragma("unroll") for (int n = 0; n < 2; ++n) _Pragma("unroll") for (int k = 0; k < 2; ++k) \
;         acc[ai][bj][m][n] = __builtin_amdgcn_mfma_f32_16x16x32_bf16(Bt[n][k], At[m][k], acc[ai][bj][m][n], 0, 0, 0); __builtin_amdgcn_s_setprio(0); } while (0)
; #define PG8_WAIT_V(n) asm volatile("s_waitcnt vmcnt(" #n ")" ::: "memory")
; #define PG8_WAIT_L(n) asm volatile("s_waitcnt lgkmcnt(" #n ")" ::: "memory")
; #define PG8_BAR __builtin_amdgcn_s_barrier()
; #define PG8_SCHED __builtin_amdgcn_sched_barrier(0)
; template <class Epi, class Sched, bool ALIGN_EPI = false, bool SP2 = false>
; __device__ __forceinline__ void gemm_phase(PG8_LAS unsigned char* lds, const Gemm g, const Sched& S, const Epi& E) {
;     ...
;             PG8_WAIT_V(8); PG8_WAIT_L(0); PG8_BAR; PG8_MMA(0, 0, At, B0); PG8_MMA(0, 1, At, B1); PG8_BAR; PG8_SCHED;
;             PG8_LDA(At, 0, 1); PG8_STAGE(PG8_SB(0, 0), b2, voffB); PG8_STAGE(PG8_SB(0, 1), b2 + hstep, voffB); PG8_STAGE(PG8_SA(0, 0), a2, voffA);
;             PG8_WAIT_V(8); PG8_WAIT_L(0); PG8_BAR; PG8_MMA(1, 0, At, B0); PG8_MMA(1, 1, At, B1); PG8_BAR; PG8_SCHED;
;             PG8_LDB(B0, 1, 0); PG8_LDB(B1, 1, 1); PG8_SCHED; PG8_LDA(At, 1, 0); PG8_STAGE(PG8_SA(0, 1), a2 + hstep, voffA);
;             PG8_WAIT_V(8); PG8_WAIT_L(0); PG8_BAR; PG8_MMA(0, 0, At, B0); PG8_MMA(0, 1, At, B1); PG8_BAR; PG8_SCHED;
	s_setprio 1
	s_waitcnt lgkmcnt(0)
	v_mfma_f32_16x16x32_bf16 v[60:63], v[132:135], v[194:197], v[60:63]
	v_mfma_f32_16x16x32_bf16 v[56:59], v[140:143], v[194:197], v[56:59]
	v_mfma_f32_16x16x32_bf16 v[44:47], v[132:135], v[202:205], v[44:47]
	v_mfma_f32_16x16x32_bf16 v[40:43], v[140:143], v[202:205], v[40:43]
	v_mfma_f32_16x16x32_bf16 v[28:31], v[132:135], v[210:213], v[28:31]
	v_mfma_f32_16x16x32_bf16 v[24:27], v[140:143], v[210:213], v[24:27]
	v_mfma_f32_16x16x32_bf16 v[12:15], v[132:135], v[218:221], v[12:15]
	v_mfma_f32_16x16x32_bf16 v[8:11], v[140:143], v[218:221], v[8:11]
	v_mfma_f32_16x16x32_bf16 v[60:63], v[136:139], v[198:201], v[60:63]
	v_mfma_f32_16x16x32_bf16 v[56:59], v[174:177], v[198:201], v[56:59]
	v_mfma_f32_16x16x32_bf16 v[44:47], v[136:139], v[206:209], v[44:47]
	v_mfma_f32_16x16x32_bf16 v[40:43], v[174:177], v[206:209], v[40:43]
	v_mfma_f32_16x16x32_bf16 v[28:31], v[136:139], v[214:217], v[28:31]
	v_mfma_f32_16x16x32_bf16 v[24:27], v[174:177], v[214:217], v[24:27]
	v_mfma_f32_16x16x32_bf16 v[12:15], v[136:139], v[222:225], v[12:15]
	v_mfma_f32_16x16x32_bf16 v[8:11], v[174:177], v[222:225], v[8:11]
	s_setprio 0
	s_setprio 1
	v_mfma_f32_16x16x32_bf16 v[52:55], v[178:181], v[194:197], v[52:55]
	v_mfma_f32_16x16x32_bf16 v[48:51], v[186:189], v[194:197], v[48:51]
	v_mfma_f32_16x16x32_bf16 v[36:39], v[178:181], v[202:205], v[36:39]
	v_mfma_f32_16x16x32_bf16 v[32:35], v[186:189], v[202:205], v[32:35]
	v_mfma_f32_16x16x32_bf16 v[20:23], v[178:181], v[210:213], v[20:23]
	v_mfma_f32_16x16x32_bf16 v[16:19], v[186:189], v[210:213], v[16:19]
	v_mfma_f32_16x16x32_bf16 v[4:7], v[178:181], v[218:221], v[4:7]
	v_mfma_f32_16x16x32_bf16 v[0:3], v[186:189], v[218:221], v[0:3]
	v_mfma_f32_16x16x32_bf16 v[52:55], v[182:185], v[198:201], v[52:55]
	v_mfma_f32_16x16x32_bf16 v[48:51], v[190:193], v[198:201], v[48:51]
	v_mfma_f32_16x16x32_bf16 v[36:39], v[182:185], v[206:209], v[36:39]
	v_mfma_f32_16x16x32_bf16 v[32:35], v[190:193], v[206:209], v[32:35]
	v_mfma_f32_16x16x32_bf16 v[20:23], v[182:185], v[214:217], v[20:23]
	v_mfma_f32_16x16x32_bf16 v[16:19], v[190:193], v[214:217], v[16:19]
	v_mfma_f32_16x16x32_bf16 v[4:7], v[182:185], v[222:225], v[4:7]
	v_mfma_f32_16x16x32_bf16 v[0:3], v[190:193], v[222:225], v[0:3]
.Lp8_skip1:
	s_setprio 0
	s_barrier
	s_add_i32 s59, 0, 0x18000
	s_add_i32 s60, 0, 0x1c000
	v_add_u32_e32 v174, s59, v167
	v_add_u32_e32 v190, s60, v167
	ds_read_b128 v[132:135], v174
	ds_read_b128 v[136:139], v174 offset:1024
	ds_read_b128 v[140:143], v174 offset:2048
	ds_read_b128 v[174:177], v174 offset:3072
	ds_read_b128 v[178:181], v190
	ds_read_b128 v[182:185], v190 offset:1024
	ds_read_b128 v[186:189], v190 offset:2048
	ds_read_b128 v[190:193], v190 offset:3072
	s_add_u32 s38, s38, 0x40000
	s_addc_u32 s39, s39, 0
	s_mov_b32 m0, s45
	v_lshl_add_u64 v[236:237], s[38:39], 0, v[152:153]
	ds_read_b128 v[194:197], v173 offset:32768
	ds_read_b128 v[198:201], v173 offset:33792
	ds_read_b128 v[202:205], v173 offset:34816
	ds_read_b128 v[206:209], v173 offset:35840
	ds_read_b128 v[210:213], v173 offset:36864
	ds_read_b128 v[214:217], v173 offset:37888
	ds_read_b128 v[218:221], v173 offset:38912
	ds_read_b128 v[222:225], v173 offset:39936
	global_load_lds_dwordx4 v[236:237], off
	v_lshl_add_u64 v[236:237], s[38:39], 0, v[148:149]
	s_mov_b32 m0, s46
	s_nop 0
	global_load_lds_dwordx4 v[236:237], off
	s_waitcnt vmcnt(8)
	s_waitcnt lgkmcnt(0)
	s_barrier
	s_setprio 1
	s_waitcnt lgkmcnt(0)
	v_mfma_f32_16x16x32_bf16 v[124:127], v[132:135], v[194:197], v[124:127]
	v_mfma_f32_16x16x32_bf16 v[120:123], v[140:143], v[194:197], v[120:123]
	v_mfma_f32_16x16x32_bf16 v[108:111], v[132:135], v[202:205], v[108:111]
	v_mfma_f32_16x16x32_bf16 v[104:107], v[140:143], v[202:205], v[104:107]
	v_mfma_f32_16x16x32_bf16 v[92:95], v[132:135], v[210:213], v[92:95]
	v_mfma_f32_16x16x32_bf16 v[88:91], v[140:143], v[210:213], v[88:91]
	v_mfma_f32_16x16x32_bf16 v[76:79], v[132:135], v[218:221], v[76:79]
	v_mfma_f32_16x16x32_bf16 v[72:75], v[140:143], v[218:221], v[72:75]
	v_mfma_f32_16x16x32_bf16 v[124:127], v[136:139], v[198:201], v[124:127]
	v_mfma_f32_16x16x32_bf16 v[120:123], v[174:177], v[198:201], v[120:123]
	v_mfma_f32_16x16x32_bf16 v[108:111], v[136:139], v[206:209], v[108:111]
	v_mfma_f32_16x16x32_bf16 v[104:107], v[174:177], v[206:209], v[104:107]
	v_mfma_f32_16x16x32_bf16 v[92:95], v[136:139], v[214:217], v[92:95]
	v_mfma_f32_16x16x32_bf16 v[88:91], v[174:177], v[214:217], v[88:91]
	v_mfma_f32_16x16x32_bf16 v[76:79], v[136:139], v[222:225], v[76:79]
	v_mfma_f32_16x16x32_bf16 v[72:75], v[174:177], v[222:225], v[72:75]
	s_setprio 0
	s_setprio 1
	v_mfma_f32_16x16x32_bf16 v[116:119], v[178:181], v[194:197], v[116:119]
	v_mfma_f32_16x16x32_bf16 v[112:115], v[186:189], v[194:197], v[112:115]
	v_mfma_f32_16x16x32_bf16 v[100:103], v[178:181], v[202:205], v[100:103]
	v_mfma_f32_16x16x32_bf16 v[96:99], v[186:189], v[202:205], v[96:99]
	v_mfma_f32_16x16x32_bf16 v[84:87], v[178:181], v[210:213], v[84:87]
	v_mfma_f32_16x16x32_bf16 v[80:83], v[186:189], v[210:213], v[80:83]
	v_mfma_f32_16x16x32_bf16 v[68:71], v[178:181], v[218:221], v[68:71]
	v_mfma_f32_16x16x32_bf16 v[64:67], v[186:189], v[218:221], v[64:67]
	v_mfma_f32_16x16x32_bf16 v[116:119], v[182:185], v[198:201], v[116:119]
	v_mfma_f32_16x16x32_bf16 v[112:115], v[190:193], v[198:201], v[112:115]
	v_mfma_f32_16x16x32_bf16 v[100:103], v[182:185], v[206:209], v[100:103]
	v_mfma_f32_16x16x32_bf16 v[96:99], v[190:193], v[206:209], v[96:99]
	v_mfma_f32_16x16x32_bf16 v[84:87], v[182:185], v[214:217], v[84:87]
	v_mfma_f32_16x16x32_bf16 v[80:83], v[190:193], v[214:217], v[80:83]
	v_mfma_f32_16x16x32_bf16 v[68:71], v[182:185], v[222:225], v[68:71]
	v_mfma_f32_16x16x32_bf16 v[64:67], v[190:193], v[222:225], v[64:67]
	s_setprio 0
	s_barrier
; #define PG8_LAS __attribute__((address_space(3)))
; #define PG8_STAGE(bufoff, gbase, voff) do { _Pragma("unroll") for (int _i = 0; _i < 2; ++_i) \
;         __builtin_amdgcn_global_load_lds((const unsigned*)((const char*)(gbase) + (voff)[_i]), (PG8_LAS unsigned*)(lds + (bufoff) + ldsw + _i * 8192), 16, 0, 0); } while (0)
; #define PG8_LDA(dst, b, h) do { _Pragma("unroll") for (int m = 0; m < 4; ++m) _Pragma("unroll") for (int k = 0; k < 2; ++k) dst[m][k] = *(const PG8_LAS bf16x8*)(lds + PG8_SA(b, h) + aoff + m * 2048 + k * 1024); } while (0)
; #define PG8_MMA(ai, bj, At, Bt) do { __builtin_amdgcn_s_setprio(1); _Pragma("unroll") for (int m = 0; m < 4; ++m) _Pragma("unroll") for (int n = 0; n < 2; ++n) _Pragma("unroll") for (int k = 0; k < 2; ++k) \
;         acc[ai][bj][m][n] = __builtin_amdgcn_mfma_f32_16x16x32_bf16(Bt[n][k], At[m][k], acc[ai][bj][m][n], 0, 0, 0); __builtin_amdgcn_s_setprio(0); } while (0)
; #define PG8_WAIT_V(n) asm volatile("s_waitcnt vmcnt(" #n ")" ::: "memory")
; #define PG8_WAIT_L(n) asm volatile("s_waitcnt lgkmcnt(" #n ")" ::: "memory")
; template <class Epi, class Sched, bool ALIGN_EPI = false, bool SP2 = false>
; __device__ __forceinline__ void gemm_phase(PG8_LAS unsigned char* lds, const Gemm g, const Sched& S, const Epi& E) {
;     ...
;             PG8_LDA(At, 1, 1); PG8_STAGE(PG8_SB(1, 0), b3, voffB); PG8_STAGE(PG8_SB(1, 1), b3 + hstep, voffB); PG8_STAGE(PG8_SA(1, 0), a3, voffA);
;             PG8_WAIT_V(8); PG8_WAIT_L(0); PG8_BAR; PG8_MMA(1, 0, At, B0); PG8_MMA(1, 1, At, B1); PG8_BAR; PG8_SCHED;
;     __device__ __forceinline__ void operator()(const f32x4 (&acc)[2][2][4][2], const Unit& u, int wr, int wc, int fr, int fq) const {
;         const int row0 = u.pm * BM + wr * 64 + fr, col0 = u.pn * HALF + wc * 32 + 8 * fq;
;         f32x4 bv[2][2];
;         if (NORM) {
; #pragma unroll
;             for (int bj = 0; bj < 2; ++bj)
; #pragma unroll
;                 for (int n = 0; n < 2; ++n) bv[bj][n] = *(const PG8_LAS f32x4*)(bl + (u.pn >> 2) * BM + bj * HALF + wc * 32 + 8 * fq + 4 * n);
;         }
; #pragma unroll
;         for (int ai = 0; ai < 2; ++ai)
; #pragma unroll
;             for (int m = 0; m < 4; ++m) {
;                 const int row = row0 + ai * HALF + m * 16;
;                 bf16_t* p = O + (size_t)row * ldc + col0;
;                 float rs = 1.f; if (NORM) rs = rsl[wr * 64 + fr + ai * HALF + m * 16];
	s_add_i32 s38, s59, s40
	v_lshl_add_u64 v[228:229], v[228:229], 0, s[12:13]
	s_mov_b32 m0, s38
	ds_read_b128 v[194:197], v173 offset:49152
	ds_read_b128 v[198:201], v173 offset:50176
	ds_read_b128 v[202:205], v173 offset:51200
	ds_read_b128 v[206:209], v173 offset:52224
	ds_read_b128 v[210:213], v173 offset:53248
	ds_read_b128 v[214:217], v173 offset:54272
	ds_read_b128 v[218:221], v173 offset:55296
	ds_read_b128 v[222:225], v173 offset:56320
	global_load_lds_dwordx4 v[228:229], off
	v_lshl_add_u64 v[228:229], v[230:231], 0, s[12:13]
	s_add_i32 m0, s38, 0x2000
	v_lshl_add_u64 v[164:165], v[164:165], 0, s[14:15]
	s_add_i32 s38, s60, s40
	global_load_lds_dwordx4 v[228:229], off
	v_lshl_add_u64 v[228:229], v[164:165], 0, v[150:151]
	s_mov_b32 m0, s38
	v_lshl_add_u64 v[164:165], v[164:165], 0, v[146:147]
	global_load_lds_dwordx4 v[228:229], off
	s_add_i32 m0, s38, 0x2000
	s_nop 0
	global_load_lds_dwordx4 v[164:165], off
	v_lshl_add_u64 v[164:165], v[232:233], 0, s[12:13]
	s_mov_b32 m0, s48
	s_nop 0
	global_load_lds_dwordx4 v[164:165], off
	v_lshl_add_u64 v[164:165], v[234:235], 0, s[12:13]
	s_mov_b32 m0, s49
	s_nop 0
	global_load_lds_dwordx4 v[164:165], off
	s_waitcnt vmcnt(8)
	s_waitcnt lgkmcnt(0)
	s_barrier
	s_cmp_lg_u32 s99, 0
	s_cbranch_scc1 .Lp8_skip3
	s_setprio 1
	s_waitcnt lgkmcnt(0)
	v_mfma_f32_16x16x32_bf16 v[60:63], v[132:135], v[194:197], v[60:63]
	v_mfma_f32_16x16x32_bf16 v[56:59], v[140:143], v[194:197], v[56:59]
	v_mfma_f32_16x16x32_bf16 v[44:47], v[132:135], v[202:205], v[44:47]
	v_mfma_f32_16x16x32_bf16 v[40:43], v[140:143], v[202:205], v[40:43]
	v_mfma_f32_16x16x32_bf16 v[28:31], v[132:135], v[210:213], v[28:31]
	v_mfma_f32_16x16x32_bf16 v[24:27], v[140:143], v[210:213], v[24:27]
	v_mfma_f32_16x16x32_bf16 v[12:15], v[132:135], v[218:221], v[12:15]
	v_mfma_f32_16x16x32_bf16 v[8:11], v[140:143], v[218:221], v[8:11]
	v_mfma_f32_16x16x32_bf16 v[60:63], v[136:139], v[198:201], v[60:63]
	v_mfma_f32_16x16x32_bf16 v[56:59], v[174:177], v[198:201], v[56:59]
	v_mfma_f32_16x16x32_bf16 v[44:47], v[136:139], v[206:209], v[44:47]
	v_mfma_f32_16x16x32_bf16 v[40:43], v[174:177], v[206:209], v[40:43]
	v_mfma_f32_16x16x32_bf16 v[28:31], v[136:139], v[214:217], v[28:31]
	v_mfma_f32_16x16x32_bf16 v[24:27], v[174:177], v[214:217], v[24:27]
	v_mfma_f32_16x16x32_bf16 v[12:15], v[136:139], v[222:225], v[12:15]
	v_mfma_f32_16x16x32_bf16 v[8:11], v[174:177], v[222:225], v[8:11]
	s_setprio 0
	s_setprio 1
	v_mfma_f32_16x16x32_bf16 v[52:55], v[178:181], v[194:197], v[52:55]
	v_mfma_f32_16x16x32_bf16 v[48:51], v[186:189], v[194:197], v[48:51]
	v_mfma_f32_16x16x32_bf16 v[36:39], v[178:181], v[202:205], v[36:39]
	v_mfma_f32_16x16x32_bf16 v[32:35], v[186:189], v[202:205], v[32:35]
	v_mfma_f32_16x16x32_bf16 v[20:23], v[178:181], v[210:213], v[20:23]
	v_mfma_f32_16x16x32_bf16 v[16:19], v[186:189], v[210:213], v[16:19]
	v_mfma_f32_16x16x32_bf16 v[4:7], v[178:181], v[218:221], v[4:7]
	v_mfma_f32_16x16x32_bf16 v[0:3], v[186:189], v[218:221], v[0:3]
	v_mfma_f32_16x16x32_bf16 v[52:55], v[182:185], v[198:201], v[52:55]
	v_mfma_f32_16x16x32_bf16 v[48:51], v[190:193], v[198:201], v[48:51]
	v_mfma_f32_16x16x32_bf16 v[36:39], v[182:185], v[206:209], v[36:39]
	v_mfma_f32_16x16x32_bf16 v[32:35], v[190:193], v[206:209], v[32:35]
	v_mfma_f32_16x16x32_bf16 v[20:23], v[182:185], v[214:217], v[20:23]
	v_mfma_f32_16x16x32_bf16 v[16:19], v[190:193], v[214:217], v[16:19]
	v_mfma_f32_16x16x32_bf16 v[4:7], v[182:185], v[222:225], v[4:7]
	v_mfma_f32_16x16x32_bf16 v[0:3], v[190:193], v[222:225], v[0:3]
.Lp8_skip3:
	s_setprio 0
	s_barrier
	s_add_i32 s21, s21, 2
	s_add_u32 s36, s36, 0x100
	s_addc_u32 s37, s37, 0
	s_cmp_gt_u32 s21, 13
	v_lshl_add_u64 v[130:131], v[130:131], 0, s[18:19]
	s_cbranch_scc0 .LBB0_907
	s_and_b64 vcc, exec, s[16:17]
	s_cbranch_vccz .LBB0_910
	s_barrier
.LBB0_910:
	v_lshl_add_u32 v253, s100, 2, v169
	s_lshl_b32 s21, s57, 8
	s_and_b32 s21, s21, 0xfffffc00
	v_add_u32_e32 v128, s21, v168
	ds_read_b128 v[140:143], v128
	ds_read_b128 v[132:135], v128 offset:16
	ds_read_b128 v[136:139], v128 offset:512
	ds_read_b128 v[128:131], v128 offset:528
	ds_read2_b32 v[178:179], v253 offset1:16
	v_lshl_or_b32 v176, s57, 7, v170
	v_lshl_add_u32 v174, s30, 8, v166
	v_add_u32_e32 v174, s100, v174
	v_ashrrev_i32_e32 v177, 31, v176
	v_mov_b64_e32 v[164:165], s[34:35]
	s_waitcnt lgkmcnt(0)
; __device__ __forceinline__ unsigned cvt_pk_bf16(float lo, float hi) { f32x2_cv v = {lo, hi}; bf16x2_cv b = __builtin_convertvector(v, bf16x2_cv); return __builtin_bit_cast(unsigned, b); }
;     __device__ __forceinline__ void operator()(const f32x4 (&acc)[2][2][4][2], const Unit& u, int wr, int wc, int fr, int fq) const {
;     ...
;                 const int row = row0 + ai * HALF + m * 16;
;                 bf16_t* p = O + (size_t)row * ldc + col0;
;                 float rs = 1.f; if (NORM) rs = rsl[wr * 64 + fr + ai * HALF + m * 16];
;                 float v[8];
; #pragma unroll
;                 for (int n = 0; n < 2; ++n) {
;                     f32x4 a4 = acc[ai][0][m][n], b4 = acc[ai][1][m][n];
;                     if (NORM) { a4 = a4 * rs + bv[0][n]; b4 = b4 * rs + bv[1][n]; }
;                     f32x4 d4 = (f32x4){__builtin_amdgcn_exp2f(-a4[0]), __builtin_amdgcn_exp2f(-a4[1]), __builtin_amdgcn_exp2f(-a4[2]), __builtin_amdgcn_exp2f(-a4[3])} + (f32x4){1.0f, 1.0f, 1.0f, 1.0f};
;                     const f32x4 r4 = (f32x4){__builtin_amdgcn_rcpf(d4[0]), __builtin_amdgcn_rcpf(d4[1]), __builtin_amdgcn_rcpf(d4[2]), __builtin_amdgcn_rcpf(d4[3])};
;                     const f32x4 o4 = (a4 * b4) * r4;
;                     v[4 * n + 0] = o4[0]; v[4 * n + 1] = o4[1]; v[4 * n + 2] = o4[2]; v[4 * n + 3] = o4[3]; }
;                 u32x4 w; w.x = cvt_pk_bf16(v[0], v[1]); w.y = cvt_pk_bf16(v[2], v[3]); w.z = cvt_pk_bf16(v[4], v[5]); w.w = cvt_pk_bf16(v[6], v[7]);
;                 *(u32x4*)p = w;
	v_pk_fma_f32 v[126:127], v[126:127], v[178:179], v[142:143] op_sel_hi:[1,0,1]
	v_pk_fma_f32 v[124:125], v[124:125], v[178:179], v[140:141] op_sel_hi:[1,0,1]
	v_pk_fma_f32 v[118:119], v[118:119], v[178:179], v[138:139] op_sel_hi:[1,0,1]
	v_pk_fma_f32 v[116:117], v[116:117], v[178:179], v[136:137] op_sel_hi:[1,0,1]
	v_pk_fma_f32 v[122:123], v[122:123], v[178:179], v[134:135] op_sel_hi:[1,0,1]
	v_pk_fma_f32 v[120:121], v[120:121], v[178:179], v[132:133] op_sel_hi:[1,0,1]
	v_exp_f32_e64 v182, -v124
	v_exp_f32_e64 v184, -v126
	v_exp_f32_e64 v185, -v127
	v_exp_f32_e64 v183, -v125
	v_pk_mul_f32 v[116:117], v[124:125], v[116:117]
	v_pk_mul_f32 v[118:119], v[126:127], v[118:119]
	v_exp_f32_e64 v124, -v120
	v_exp_f32_e64 v126, -v122
	v_exp_f32_e64 v127, -v123
	v_exp_f32_e64 v125, -v121
	v_pk_add_f32 v[184:185], v[184:185], 1.0 op_sel_hi:[1,0]
	v_pk_add_f32 v[182:183], v[182:183], 1.0 op_sel_hi:[1,0]
	v_pk_add_f32 v[126:127], v[126:127], 1.0 op_sel_hi:[1,0]
	v_pk_add_f32 v[124:125], v[124:125], 1.0 op_sel_hi:[1,0]
	v_rcp_f32_e32 v182, v182
	v_rcp_f32_e32 v184, v184
	v_rcp_f32_e32 v185, v185
	v_rcp_f32_e32 v183, v183
	v_rcp_f32_e32 v124, v124
	v_rcp_f32_e32 v126, v126
	v_rcp_f32_e32 v127, v127
	v_rcp_f32_e32 v125, v125
	v_pk_fma_f32 v[114:115], v[114:115], v[178:179], v[130:131] op_sel_hi:[1,0,1]
	v_pk_fma_f32 v[112:113], v[112:113], v[178:179], v[128:129] op_sel_hi:[1,0,1]
	v_pk_mul_f32 v[114:115], v[122:123], v[114:115]
	v_pk_mul_f32 v[112:113], v[120:121], v[112:113]
	v_mad_i64_i32 v[180:181], s[36:37], v174, s54, v[164:165]
	v_pk_mul_f32 v[118:119], v[118:119], v[184:185]
	v_pk_mul_f32 v[116:117], v[116:117], v[182:183]
	v_pk_mul_f32 v[120:121], v[114:115], v[126:127]
	v_pk_mul_f32 v[122:123], v[112:113], v[124:125]
	v_lshlrev_b64 v[112:113], 1, v[176:177]
	v_lshl_add_u64 v[124:125], v[180:181], 0, v[112:113]
	v_cvt_pk_bf16_f32 v114, v116, v117
	v_cvt_pk_bf16_f32 v115, v118, v119
	v_cvt_pk_bf16_f32 v116, v122, v123
	v_cvt_pk_bf16_f32 v117, v120, v121
	global_store_dwordx4 v[124:125], v[114:117], off
	s_andn2_b64 vcc, exec, s[4:5]
	s_mov_b64 s[4:5], -1
	v_mov_b32_e32 v116, v179
	v_pk_fma_f32 v[108:109], v[108:109], v[116:117], v[140:141] op_sel_hi:[1,0,1]
	v_pk_fma_f32 v[110:111], v[110:111], v[116:117], v[142:143] op_sel_hi:[1,0,1]
	v_exp_f32_e64 v118, -v108
	v_exp_f32_e64 v119, -v109
	v_pk_fma_f32 v[102:103], v[102:103], v[116:117], v[138:139] op_sel_hi:[1,0,1]
	v_pk_fma_f32 v[100:101], v[100:101], v[116:117], v[136:137] op_sel_hi:[1,0,1]
	v_pk_fma_f32 v[106:107], v[106:107], v[116:117], v[134:135] op_sel_hi:[1,0,1]
	v_pk_fma_f32 v[104:105], v[104:105], v[116:117], v[132:133] op_sel_hi:[1,0,1]
	v_exp_f32_e64 v120, -v110
	v_exp_f32_e64 v121, -v111
	v_pk_mul_f32 v[100:101], v[108:109], v[100:101]
	v_pk_mul_f32 v[102:103], v[110:111], v[102:103]
	v_exp_f32_e64 v108, -v104
	v_exp_f32_e64 v110, -v106
	v_exp_f32_e64 v111, -v107
	v_exp_f32_e64 v109, -v105
	v_pk_add_f32 v[118:119], v[118:119], 1.0 op_sel_hi:[1,0]
	v_pk_fma_f32 v[98:99], v[98:99], v[116:117], v[130:131] op_sel_hi:[1,0,1]
	v_rcp_f32_e32 v118, v118
	v_rcp_f32_e32 v119, v119
	v_pk_add_f32 v[110:111], v[110:111], 1.0 op_sel_hi:[1,0]
	v_pk_add_f32 v[108:109], v[108:109], 1.0 op_sel_hi:[1,0]
	v_rcp_f32_e32 v110, v110
	v_rcp_f32_e32 v108, v108
	v_rcp_f32_e32 v111, v111
	v_rcp_f32_e32 v109, v109
	v_pk_fma_f32 v[96:97], v[96:97], v[116:117], v[128:129] op_sel_hi:[1,0,1]
	v_pk_add_f32 v[120:121], v[120:121], 1.0 op_sel_hi:[1,0]
	v_pk_mul_f32 v[100:101], v[100:101], v[118:119]
	v_pk_mul_f32 v[96:97], v[104:105], v[96:97]
	v_pk_mul_f32 v[98:99], v[106:107], v[98:99]
	v_rcp_f32_e32 v120, v120
	v_rcp_f32_e32 v121, v121
	v_pk_mul_f32 v[104:105], v[98:99], v[110:111]
	v_pk_mul_f32 v[98:99], v[96:97], v[108:109]
	v_cvt_pk_bf16_f32 v96, v100, v101
	ds_read2_b32 v[100:101], v253 offset0:32 offset1:48
	v_or_b32_e32 v114, 16, v174
	v_mad_i64_i32 v[114:115], s[36:37], v114, s54, v[164:165]
	v_pk_mul_f32 v[102:103], v[102:103], v[120:121]
	v_lshl_add_u64 v[106:107], v[114:115], 0, v[112:113]
	v_cvt_pk_bf16_f32 v97, v102, v103
	v_cvt_pk_bf16_f32 v98, v98, v99
	v_cvt_pk_bf16_f32 v99, v104, v105
	s_waitcnt lgkmcnt(0)
	v_pk_fma_f32 v[94:95], v[94:95], v[100:101], v[142:143] op_sel_hi:[1,0,1]
	v_pk_fma_f32 v[92:93], v[92:93], v[100:101], v[140:141] op_sel_hi:[1,0,1]
	v_pk_fma_f32 v[86:87], v[86:87], v[100:101], v[138:139] op_sel_hi:[1,0,1]
	v_pk_fma_f32 v[84:85], v[84:85], v[100:101], v[136:137] op_sel_hi:[1,0,1]
	v_pk_fma_f32 v[90:91], v[90:91], v[100:101], v[134:135] op_sel_hi:[1,0,1]
	v_pk_fma_f32 v[88:89], v[88:89], v[100:101], v[132:133] op_sel_hi:[1,0,1]
	global_store_dwordx4 v[106:107], v[96:99], off
	v_exp_f32_e64 v102, -v94
	v_exp_f32_e64 v103, -v95
	v_exp_f32_e64 v98, -v92
	v_exp_f32_e64 v99, -v93
	v_pk_mul_f32 v[84:85], v[92:93], v[84:85]
	v_pk_mul_f32 v[86:87], v[94:95], v[86:87]
	v_exp_f32_e64 v92, -v88
	v_exp_f32_e64 v94, -v90
	v_exp_f32_e64 v95, -v91
	v_exp_f32_e64 v93, -v89
	v_pk_add_f32 v[102:103], v[102:103], 1.0 op_sel_hi:[1,0]
	v_pk_add_f32 v[98:99], v[98:99], 1.0 op_sel_hi:[1,0]
	v_pk_add_f32 v[94:95], v[94:95], 1.0 op_sel_hi:[1,0]
	v_pk_add_f32 v[92:93], v[92:93], 1.0 op_sel_hi:[1,0]
	v_rcp_f32_e32 v98, v98
	v_rcp_f32_e32 v102, v102
	v_rcp_f32_e32 v103, v103
	v_rcp_f32_e32 v99, v99
	v_rcp_f32_e32 v92, v92
	v_rcp_f32_e32 v94, v94
	v_rcp_f32_e32 v95, v95
	v_rcp_f32_e32 v93, v93
	v_pk_fma_f32 v[82:83], v[82:83], v[100:101], v[130:131] op_sel_hi:[1,0,1]
	v_pk_fma_f32 v[80:81], v[80:81], v[100:101], v[128:129] op_sel_hi:[1,0,1]
	v_or_b32_e32 v96, 32, v174
	v_pk_mul_f32 v[80:81], v[88:89], v[80:81]
	v_pk_mul_f32 v[82:83], v[90:91], v[82:83]
	v_mad_i64_i32 v[96:97], s[36:37], v96, s54, v[164:165]
; __device__ __forceinline__ unsigned cvt_pk_bf16(float lo, float hi) { f32x2_cv v = {lo, hi}; bf16x2_cv b = __builtin_convertvector(v, bf16x2_cv); return __builtin_bit_cast(unsigned, b); }
;     __device__ __forceinline__ void operator()(const f32x4 (&acc)[2][2][4][2], const Unit& u, int wr, int wc, int fr, int fq) const {
;     ...
;                 for (int n = 0; n < 2; ++n) {
;                     f32x4 a4 = acc[ai][0][m][n], b4 = acc[ai][1][m][n];
;                     if (NORM) { a4 = a4 * rs + bv[0][n]; b4 = b4 * rs + bv[1][n]; }
;                     f32x4 d4 = (f32x4){__builtin_amdgcn_exp2f(-a4[0]), __builtin_amdgcn_exp2f(-a4[1]), __builtin_amdgcn_exp2f(-a4[2]), __builtin_amdgcn_exp2f(-a4[3])} + (f32x4){1.0f, 1.0f, 1.0f, 1.0f};
;                     const f32x4 r4 = (f32x4){__builtin_amdgcn_rcpf(d4[0]), __builtin_amdgcn_rcpf(d4[1]), __builtin_amdgcn_rcpf(d4[2]), __builtin_amdgcn_rcpf(d4[3])};
;                     const f32x4 o4 = (a4 * b4) * r4;
;                     v[4 * n + 0] = o4[0]; v[4 * n + 1] = o4[1]; v[4 * n + 2] = o4[2]; v[4 * n + 3] = o4[3]; }
;                 u32x4 w; w.x = cvt_pk_bf16(v[0], v[1]); w.y = cvt_pk_bf16(v[2], v[3]); w.z = cvt_pk_bf16(v[4], v[5]); w.w = cvt_pk_bf16(v[6], v[7]);
;                 *(u32x4*)p = w;
	v_pk_mul_f32 v[86:87], v[86:87], v[102:103]
	v_pk_mul_f32 v[84:85], v[84:85], v[98:99]
	v_pk_mul_f32 v[88:89], v[82:83], v[94:95]
	v_pk_mul_f32 v[82:83], v[80:81], v[92:93]
	v_lshl_add_u64 v[90:91], v[96:97], 0, v[112:113]
	v_cvt_pk_bf16_f32 v80, v84, v85
	v_cvt_pk_bf16_f32 v81, v86, v87
	v_cvt_pk_bf16_f32 v82, v82, v83
	v_cvt_pk_bf16_f32 v83, v88, v89
	global_store_dwordx4 v[90:91], v[80:83], off
	s_nop 1
	v_mov_b32_e32 v82, v101
	v_pk_fma_f32 v[76:77], v[76:77], v[82:83], v[140:141] op_sel_hi:[1,0,1]
	v_pk_fma_f32 v[78:79], v[78:79], v[82:83], v[142:143] op_sel_hi:[1,0,1]
	v_exp_f32_e64 v84, -v76
	v_exp_f32_e64 v85, -v77
	v_pk_fma_f32 v[70:71], v[70:71], v[82:83], v[138:139] op_sel_hi:[1,0,1]
	v_pk_fma_f32 v[68:69], v[68:69], v[82:83], v[136:137] op_sel_hi:[1,0,1]
	v_pk_fma_f32 v[74:75], v[74:75], v[82:83], v[134:135] op_sel_hi:[1,0,1]
	v_pk_fma_f32 v[72:73], v[72:73], v[82:83], v[132:133] op_sel_hi:[1,0,1]
	v_exp_f32_e64 v86, -v78
	v_exp_f32_e64 v87, -v79
	v_pk_mul_f32 v[68:69], v[76:77], v[68:69]
	v_pk_mul_f32 v[70:71], v[78:79], v[70:71]
	v_exp_f32_e64 v76, -v72
	v_exp_f32_e64 v78, -v74
	v_exp_f32_e64 v79, -v75
	v_exp_f32_e64 v77, -v73
	v_pk_add_f32 v[84:85], v[84:85], 1.0 op_sel_hi:[1,0]
	v_pk_fma_f32 v[66:67], v[66:67], v[82:83], v[130:131] op_sel_hi:[1,0,1]
	v_rcp_f32_e32 v84, v84
	v_rcp_f32_e32 v85, v85
	v_pk_add_f32 v[78:79], v[78:79], 1.0 op_sel_hi:[1,0]
	v_pk_add_f32 v[76:77], v[76:77], 1.0 op_sel_hi:[1,0]
	v_rcp_f32_e32 v78, v78
	v_rcp_f32_e32 v76, v76
	v_rcp_f32_e32 v79, v79
	v_rcp_f32_e32 v77, v77
	v_pk_fma_f32 v[64:65], v[64:65], v[82:83], v[128:129] op_sel_hi:[1,0,1]
	v_pk_add_f32 v[86:87], v[86:87], 1.0 op_sel_hi:[1,0]
	v_pk_mul_f32 v[68:69], v[68:69], v[84:85]
	v_pk_mul_f32 v[64:65], v[72:73], v[64:65]
	v_pk_mul_f32 v[66:67], v[74:75], v[66:67]
	v_rcp_f32_e32 v86, v86
	v_rcp_f32_e32 v87, v87
	v_pk_mul_f32 v[72:73], v[66:67], v[78:79]
	v_pk_mul_f32 v[66:67], v[64:65], v[76:77]
	v_cvt_pk_bf16_f32 v64, v68, v69
	ds_read2_b32 v[68:69], v169 offset0:128 offset1:144
	v_or_b32_e32 v80, 48, v174
	v_mad_i64_i32 v[80:81], s[36:37], v80, s54, v[164:165]
	v_pk_mul_f32 v[70:71], v[70:71], v[86:87]
	v_lshl_add_u64 v[74:75], v[80:81], 0, v[112:113]
	v_cvt_pk_bf16_f32 v65, v70, v71
	v_cvt_pk_bf16_f32 v66, v66, v67
	v_cvt_pk_bf16_f32 v67, v72, v73
	s_waitcnt lgkmcnt(0)
	v_pk_fma_f32 v[62:63], v[62:63], v[68:69], v[142:143] op_sel_hi:[1,0,1]
	v_pk_fma_f32 v[60:61], v[60:61], v[68:69], v[140:141] op_sel_hi:[1,0,1]
	v_pk_fma_f32 v[54:55], v[54:55], v[68:69], v[138:139] op_sel_hi:[1,0,1]
	v_pk_fma_f32 v[52:53], v[52:53], v[68:69], v[136:137] op_sel_hi:[1,0,1]
	v_pk_fma_f32 v[58:59], v[58:59], v[68:69], v[134:135] op_sel_hi:[1,0,1]
	v_pk_fma_f32 v[56:57], v[56:57], v[68:69], v[132:133] op_sel_hi:[1,0,1]
	global_store_dwordx4 v[74:75], v[64:67], off
	s_cmp_lg_u32 s99, 0
	s_cbranch_scc1 .Lp8_epi_half
	v_exp_f32_e64 v70, -v62
	v_exp_f32_e64 v71, -v63
	v_exp_f32_e64 v66, -v60
	v_exp_f32_e64 v67, -v61
	v_pk_mul_f32 v[52:53], v[60:61], v[52:53]
	v_pk_mul_f32 v[54:55], v[62:63], v[54:55]
	v_exp_f32_e64 v60, -v56
	v_exp_f32_e64 v62, -v58
	v_exp_f32_e64 v63, -v59
	v_exp_f32_e64 v61, -v57
	v_pk_add_f32 v[70:71], v[70:71], 1.0 op_sel_hi:[1,0]
	v_pk_add_f32 v[66:67], v[66:67], 1.0 op_sel_hi:[1,0]
	v_pk_add_f32 v[62:63], v[62:63], 1.0 op_sel_hi:[1,0]
	v_pk_add_f32 v[60:61], v[60:61], 1.0 op_sel_hi:[1,0]
	v_rcp_f32_e32 v66, v66
	v_rcp_f32_e32 v70, v70
	v_rcp_f32_e32 v71, v71
	v_rcp_f32_e32 v67, v67
	v_rcp_f32_e32 v60, v60
	v_rcp_f32_e32 v62, v62
	v_rcp_f32_e32 v63, v63
	v_rcp_f32_e32 v61, v61
	v_pk_fma_f32 v[50:51], v[50:51], v[68:69], v[130:131] op_sel_hi:[1,0,1]
	v_pk_fma_f32 v[48:49], v[48:49], v[68:69], v[128:129] op_sel_hi:[1,0,1]
	v_add_u32_e32 v64, 0x80, v174
	v_pk_mul_f32 v[48:49], v[56:57], v[48:49]
	v_pk_mul_f32 v[50:51], v[58:59], v[50:51]
	v_mad_i64_i32 v[64:65], s[36:37], v64, s54, v[164:165]
	v_pk_mul_f32 v[54:55], v[54:55], v[70:71]
	v_pk_mul_f32 v[52:53], v[52:53], v[66:67]
	v_pk_mul_f32 v[56:57], v[50:51], v[62:63]
	v_pk_mul_f32 v[50:51], v[48:49], v[60:61]
	v_lshl_add_u64 v[58:59], v[64:65], 0, v[112:113]
	v_cvt_pk_bf16_f32 v48, v52, v53
	v_cvt_pk_bf16_f32 v49, v54, v55
	v_cvt_pk_bf16_f32 v50, v50, v51
	v_cvt_pk_bf16_f32 v51, v56, v57
	global_store_dwordx4 v[58:59], v[48:51], off
	s_nop 1
	v_mov_b32_e32 v50, v69
	v_pk_fma_f32 v[44:45], v[44:45], v[50:51], v[140:141] op_sel_hi:[1,0,1]
	v_pk_fma_f32 v[46:47], v[46:47], v[50:51], v[142:143] op_sel_hi:[1,0,1]
	v_exp_f32_e64 v52, -v44
	v_exp_f32_e64 v53, -v45
	v_pk_fma_f32 v[38:39], v[38:39], v[50:51], v[138:139] op_sel_hi:[1,0,1]
	v_pk_fma_f32 v[36:37], v[36:37], v[50:51], v[136:137] op_sel_hi:[1,0,1]
	v_pk_fma_f32 v[42:43], v[42:43], v[50:51], v[134:135] op_sel_hi:[1,0,1]
	v_pk_fma_f32 v[40:41], v[40:41], v[50:51], v[132:133] op_sel_hi:[1,0,1]
	v_exp_f32_e64 v54, -v46
	v_exp_f32_e64 v55, -v47
	v_pk_mul_f32 v[36:37], v[44:45], v[36:37]
	v_pk_mul_f32 v[38:39], v[46:47], v[38:39]
	v_exp_f32_e64 v44, -v40
	v_exp_f32_e64 v46, -v42
	v_exp_f32_e64 v47, -v43
	v_exp_f32_e64 v45, -v41
	v_pk_add_f32 v[52:53], v[52:53], 1.0 op_sel_hi:[1,0]
	v_pk_fma_f32 v[34:35], v[34:35], v[50:51], v[130:131] op_sel_hi:[1,0,1]
	v_rcp_f32_e32 v52, v52
	v_rcp_f32_e32 v53, v53
	v_pk_add_f32 v[46:47], v[46:47], 1.0 op_sel_hi:[1,0]
	v_pk_add_f32 v[44:45], v[44:45], 1.0 op_sel_hi:[1,0]
	v_rcp_f32_e32 v46, v46
	v_rcp_f32_e32 v44, v44
	v_rcp_f32_e32 v47, v47
	v_rcp_f32_e32 v45, v45
	v_pk_fma_f32 v[32:33], v[32:33], v[50:51], v[128:129] op_sel_hi:[1,0,1]
	v_pk_add_f32 v[54:55], v[54:55], 1.0 op_sel_hi:[1,0]
	v_pk_mul_f32 v[36:37], v[36:37], v[52:53]
	v_pk_mul_f32 v[32:33], v[40:41], v[32:33]
	v_pk_mul_f32 v[34:35], v[42:43], v[34:35]
	v_rcp_f32_e32 v54, v54
	v_rcp_f32_e32 v55, v55
	v_pk_mul_f32 v[40:41], v[34:35], v[46:47]
	v_pk_mul_f32 v[34:35], v[32:33], v[44:45]
	v_cvt_pk_bf16_f32 v32, v36, v37
	ds_read2_b32 v[36:37], v169 offset0:160 offset1:176
	v_add_u32_e32 v48, 0x90, v174
	v_mad_i64_i32 v[48:49], s[36:37], v48, s54, v[164:165]
	v_pk_mul_f32 v[38:39], v[38:39], v[54:55]
	v_lshl_add_u64 v[42:43], v[48:49], 0, v[112:113]
	v_cvt_pk_bf16_f32 v33, v38, v39
	v_cvt_pk_bf16_f32 v34, v34, v35
	v_cvt_pk_bf16_f32 v35, v40, v41
	s_waitcnt lgkmcnt(0)
; __device__ __forceinline__ unsigned cvt_pk_bf16(float lo, float hi) { f32x2_cv v = {lo, hi}; bf16x2_cv b = __builtin_convertvector(v, bf16x2_cv); return __builtin_bit_cast(unsigned, b); }
;     __device__ __forceinline__ void operator()(const f32x4 (&acc)[2][2][4][2], const Unit& u, int wr, int wc, int fr, int fq) const {
;     ...
;                 for (int n = 0; n < 2; ++n) {
;                     f32x4 a4 = acc[ai][0][m][n], b4 = acc[ai][1][m][n];
;                     if (NORM) { a4 = a4 * rs + bv[0][n]; b4 = b4 * rs + bv[1][n]; }
;                     f32x4 d4 = (f32x4){__builtin_amdgcn_exp2f(-a4[0]), __builtin_amdgcn_exp2f(-a4[1]), __builtin_amdgcn_exp2f(-a4[2]), __builtin_amdgcn_exp2f(-a4[3])} + (f32x4){1.0f, 1.0f, 1.0f, 1.0f};
;                     const f32x4 r4 = (f32x4){__builtin_amdgcn_rcpf(d4[0]), __builtin_amdgcn_rcpf(d4[1]), __builtin_amdgcn_rcpf(d4[2]), __builtin_amdgcn_rcpf(d4[3])};
;                     const f32x4 o4 = (a4 * b4) * r4;
;                     v[4 * n + 0] = o4[0]; v[4 * n + 1] = o4[1]; v[4 * n + 2] = o4[2]; v[4 * n + 3] = o4[3]; }
;                 u32x4 w; w.x = cvt_pk_bf16(v[0], v[1]); w.y = cvt_pk_bf16(v[2], v[3]); w.z = cvt_pk_bf16(v[4], v[5]); w.w = cvt_pk_bf16(v[6], v[7]);
;                 *(u32x4*)p = w;
	v_pk_fma_f32 v[30:31], v[30:31], v[36:37], v[142:143] op_sel_hi:[1,0,1]
	v_pk_fma_f32 v[28:29], v[28:29], v[36:37], v[140:141] op_sel_hi:[1,0,1]
	v_pk_fma_f32 v[22:23], v[22:23], v[36:37], v[138:139] op_sel_hi:[1,0,1]
	v_pk_fma_f32 v[20:21], v[20:21], v[36:37], v[136:137] op_sel_hi:[1,0,1]
	v_pk_fma_f32 v[26:27], v[26:27], v[36:37], v[134:135] op_sel_hi:[1,0,1]
	v_pk_fma_f32 v[24:25], v[24:25], v[36:37], v[132:133] op_sel_hi:[1,0,1]
	global_store_dwordx4 v[42:43], v[32:35], off
	v_exp_f32_e64 v38, -v30
	v_exp_f32_e64 v39, -v31
	v_exp_f32_e64 v34, -v28
	v_exp_f32_e64 v35, -v29
	v_pk_mul_f32 v[20:21], v[28:29], v[20:21]
	v_pk_mul_f32 v[22:23], v[30:31], v[22:23]
	v_exp_f32_e64 v28, -v24
	v_exp_f32_e64 v30, -v26
	v_exp_f32_e64 v31, -v27
	v_exp_f32_e64 v29, -v25
	v_pk_add_f32 v[38:39], v[38:39], 1.0 op_sel_hi:[1,0]
	v_pk_add_f32 v[34:35], v[34:35], 1.0 op_sel_hi:[1,0]
	v_pk_add_f32 v[30:31], v[30:31], 1.0 op_sel_hi:[1,0]
	v_pk_add_f32 v[28:29], v[28:29], 1.0 op_sel_hi:[1,0]
	v_rcp_f32_e32 v34, v34
	v_rcp_f32_e32 v38, v38
	v_rcp_f32_e32 v39, v39
	v_rcp_f32_e32 v35, v35
	v_rcp_f32_e32 v28, v28
	v_rcp_f32_e32 v30, v30
	v_rcp_f32_e32 v31, v31
	v_rcp_f32_e32 v29, v29
	v_pk_fma_f32 v[18:19], v[18:19], v[36:37], v[130:131] op_sel_hi:[1,0,1]
	v_pk_fma_f32 v[16:17], v[16:17], v[36:37], v[128:129] op_sel_hi:[1,0,1]
	v_add_u32_e32 v32, 0xa0, v174
	v_pk_mul_f32 v[16:17], v[24:25], v[16:17]
	v_pk_mul_f32 v[18:19], v[26:27], v[18:19]
	v_mad_i64_i32 v[32:33], s[36:37], v32, s54, v[164:165]
	v_pk_mul_f32 v[22:23], v[22:23], v[38:39]
	v_pk_mul_f32 v[20:21], v[20:21], v[34:35]
	v_pk_mul_f32 v[24:25], v[18:19], v[30:31]
	v_pk_mul_f32 v[18:19], v[16:17], v[28:29]
	v_lshl_add_u64 v[26:27], v[32:33], 0, v[112:113]
	v_cvt_pk_bf16_f32 v16, v20, v21
	v_cvt_pk_bf16_f32 v17, v22, v23
	v_cvt_pk_bf16_f32 v18, v18, v19
	v_cvt_pk_bf16_f32 v19, v24, v25
	global_store_dwordx4 v[26:27], v[16:19], off
	s_nop 1
	v_mov_b32_e32 v18, v37
	v_pk_fma_f32 v[14:15], v[14:15], v[18:19], v[142:143] op_sel_hi:[1,0,1]
	v_pk_fma_f32 v[12:13], v[12:13], v[18:19], v[140:141] op_sel_hi:[1,0,1]
	v_pk_fma_f32 v[6:7], v[6:7], v[18:19], v[138:139] op_sel_hi:[1,0,1]
	v_pk_fma_f32 v[4:5], v[4:5], v[18:19], v[136:137] op_sel_hi:[1,0,1]
	v_pk_fma_f32 v[10:11], v[10:11], v[18:19], v[134:135] op_sel_hi:[1,0,1]
	v_pk_fma_f32 v[8:9], v[8:9], v[18:19], v[132:133] op_sel_hi:[1,0,1]
	v_exp_f32_e64 v20, -v12
	v_exp_f32_e64 v22, -v14
	v_exp_f32_e64 v23, -v15
	v_exp_f32_e64 v21, -v13
	v_pk_mul_f32 v[4:5], v[12:13], v[4:5]
	v_pk_mul_f32 v[6:7], v[14:15], v[6:7]
	v_exp_f32_e64 v12, -v8
	v_exp_f32_e64 v14, -v10
	v_exp_f32_e64 v15, -v11
	v_exp_f32_e64 v13, -v9
	v_pk_add_f32 v[22:23], v[22:23], 1.0 op_sel_hi:[1,0]
	v_pk_add_f32 v[20:21], v[20:21], 1.0 op_sel_hi:[1,0]
	v_pk_add_f32 v[14:15], v[14:15], 1.0 op_sel_hi:[1,0]
	v_pk_add_f32 v[12:13], v[12:13], 1.0 op_sel_hi:[1,0]
	v_rcp_f32_e32 v20, v20
	v_rcp_f32_e32 v22, v22
	v_rcp_f32_e32 v23, v23
	v_rcp_f32_e32 v21, v21
	v_rcp_f32_e32 v12, v12
	v_rcp_f32_e32 v14, v14
	v_rcp_f32_e32 v15, v15
	v_rcp_f32_e32 v13, v13
	v_pk_fma_f32 v[2:3], v[2:3], v[18:19], v[130:131] op_sel_hi:[1,0,1]
	v_pk_fma_f32 v[0:1], v[0:1], v[18:19], v[128:129] op_sel_hi:[1,0,1]
	v_add_u32_e32 v16, 0xb0, v174
	v_pk_mul_f32 v[0:1], v[8:9], v[0:1]
	v_pk_mul_f32 v[2:3], v[10:11], v[2:3]
	v_mad_i64_i32 v[16:17], s[36:37], v16, s54, v[164:165]
	v_pk_mul_f32 v[6:7], v[6:7], v[22:23]
	v_pk_mul_f32 v[4:5], v[4:5], v[20:21]
	v_pk_mul_f32 v[8:9], v[2:3], v[14:15]
	v_pk_mul_f32 v[2:3], v[0:1], v[12:13]
	v_lshl_add_u64 v[10:11], v[16:17], 0, v[112:113]
	v_cvt_pk_bf16_f32 v0, v4, v5
	v_cvt_pk_bf16_f32 v1, v6, v7
	v_cvt_pk_bf16_f32 v2, v2, v3
	v_cvt_pk_bf16_f32 v3, v8, v9
	global_store_dwordx4 v[10:11], v[0:3], off
.Lp8_epi_half:
	s_cbranch_vccnz .LBB0_903
	s_andn2_b64 vcc, exec, s[10:11]
	s_cbranch_vccnz .LBB0_902
	s_barrier
	s_branch .LBB0_902
